# RNN loop: bank-conflict-free padded layout for the (a,v) scan tile (row stride 1088 B, 16 B pad per 256 B)
# speedup vs baseline: 1.0046x; 1.0046x over previous
.LBB0_109:
	s_or_b64 exec, exec, s[10:11]
	s_lshl_b64 s[20:21], s[0:1], 12
	s_add_u32 s0, s16, s20
	s_addc_u32 s1, s17, s21
	s_add_u32 s0, s0, s6
	s_addc_u32 s1, s1, 0
	s_add_u32 s0, s0, s7
	v_ashrrev_i32_e32 v0, 6, v182
	s_addc_u32 s1, s1, 0
	v_mov_b32_e32 v171, v1
	v_lshlrev_b32_e32 v148, 1, v168
	v_lshl_or_b32 v142, v0, 2, v213
	v_lshl_add_u64 v[146:147], s[0:1], 0, v[170:171]
	v_lshl_add_u64 v[2:3], s[26:27], 0, v[170:171]
	v_add_u32_e32 v171, s52, v148
	v_lshlrev_b32_e32 v0, 4, v0
	s_movk_i32 s6, 0x420
	v_add3_u32 v143, v213, v141, v0
	v_or_b32_e32 v220, v0, v141
	v_lshl_add_u32 v224, v141, 6, s98
	v_mul_lo_u32 v225, v142, s6
	v_mul_lo_u32 v142, v142, s51
	v_lshlrev_b32_e32 v0, 4, v141
	v_mad_u32_u24 v141, v183, s51, v171
	v_mul_lo_u32 v150, v143, s51
	v_add_u32_e32 v226, s99, v142
	v_add_u32_e32 v227, s52, v142
	ds_read_u16 v142, v141
	ds_read_u16 v151, v141 offset:272
	ds_read_u16 v143, v141 offset:544
	ds_read_u16 v153, v141 offset:816
	ds_read_u16 v144, v141 offset:1088
	ds_read_u16 v155, v141 offset:1360
	ds_read_u16 v145, v141 offset:1632
	ds_read_u16 v141, v141 offset:1904
	v_lshlrev_b64 v[184:185], 12, v[168:169]
	v_mad_u32_u24 v152, v183, s51, v252
	s_waitcnt lgkmcnt(4)
	v_perm_b32 v143, v153, v143, s8
	s_waitcnt lgkmcnt(2)
	v_perm_b32 v144, v155, v144, s8
	s_waitcnt lgkmcnt(0)
	v_perm_b32 v145, v141, v145, s8
	v_mov_b32_e32 v141, s99
	v_mad_u32_u24 v141, v183, s51, v141
	v_perm_b32 v142, v151, v142, s8
	v_lshl_add_u64 v[146:147], v[146:147], 0, v[184:185]
	v_add_u32_e32 v175, v141, v148
	global_store_dwordx4 v[146:147], v[142:145], off
	ds_write_b16 v175, v120
	ds_write_b16_d16_hi v175, v120 offset:272
	v_add_u32_e32 v120, s99, v152
	v_add_u32_e32 v200, s99, v148
	v_mad_u32_u24 v154, v183, s51, v194
	v_add_u32_e32 v141, v200, v152
	v_add_u32_e32 v201, v120, v148
	v_mad_u32_u24 v156, v183, s51, v195
	ds_write_b16 v141, v121
	ds_write_b16_d16_hi v201, v121 offset:272
	v_add_u32_e32 v120, s99, v154
	v_add_u32_e32 v121, v200, v154
	ds_write_b16 v121, v122
	v_add_u32_e32 v202, v120, v148
	v_add_u32_e32 v120, s99, v156
	v_add_u32_e32 v121, v200, v156
	v_and_b32_e32 v149, 48, v182
	ds_write_b16 v121, v123
	v_add_u32_e32 v203, v120, v148
	v_lshlrev_b64 v[120:121], 11, v[168:169]
	v_lshl_add_u64 v[120:121], v[2:3], 0, v[120:121]
	s_mov_b32 s6, 0x40000
	v_add_u32_e32 v141, 0, v149
	ds_write_b16_d16_hi v202, v122 offset:272
	ds_write_b16_d16_hi v203, v123 offset:272
	v_add_co_u32_e32 v120, vcc, s6, v120
	v_add_u32_e32 v204, 0x19c00, v141
	s_nop 0
	v_addc_co_u32_e32 v121, vcc, 0, v121, vcc
	ds_read_b128 v[142:145], v204
	global_load_dwordx4 v[120:123], v[120:121], off
	v_add_u32_e32 v205, 0, v150
	ds_read_b128 v[146:149], v204 offset:64
	ds_read_b128 v[150:153], v205
	ds_read_b128 v[154:157], v205 offset:16
	ds_read_b128 v[158:161], v205 offset:32
	ds_read_b128 v[162:165], v205 offset:48
	s_waitcnt lgkmcnt(3)
	v_mfma_f32_16x16x32_bf16 v[142:145], v[4:7], v[150:153], v[142:145]
	s_cmp_eq_u32 s28, 0
	s_cselect_b64 vcc, -1, 0
	s_cmp_eq_u32 s28, 1
	s_waitcnt lgkmcnt(1)
	v_mfma_f32_16x16x32_bf16 v[146:149], v[12:15], v[158:161], v[146:149]
	s_cselect_b64 s[40:41], -1, 0
	s_cmp_eq_u32 s28, 2
	s_cselect_b64 s[42:43], -1, 0
	v_mfma_f32_16x16x32_bf16 v[142:145], v[8:11], v[154:157], v[142:145]
	s_cmp_eq_u32 s28, 3
	s_cselect_b64 s[44:45], -1, 0
	s_add_i32 s6, 0, 0x19800
	s_waitcnt lgkmcnt(0)
	v_mfma_f32_16x16x32_bf16 v[146:149], v[16:19], v[162:165], v[146:149]
	v_add_u32_e32 v224, v224, v225
	s_nop 1
	v_cvt_pk_bf16_f32 v142, v142, v143
	v_cvt_pk_bf16_f32 v143, v144, v145
	v_cndmask_b32_e32 v167, 0, v142, vcc
	v_cndmask_b32_e32 v190, 0, v143, vcc
	s_nop 0
	v_cvt_pk_bf16_f32 v144, v146, v147
	v_cvt_pk_bf16_f32 v145, v148, v149
	v_cndmask_b32_e32 v141, 0, v144, vcc
	v_cndmask_b32_e32 v166, 0, v145, vcc
	v_mfma_f32_16x16x32_bf16 v[146:149], v[52:55], v[142:145], 0
	v_add_u32_e32 v226, v226, v0
	v_add_u32_e32 v227, v227, v0
	v_mfma_f32_16x16x32_bf16 v[150:153], v[68:71], v[142:145], 0
	v_mfma_f32_16x16x32_bf16 v[154:157], v[84:87], v[142:145], 0
	v_mfma_f32_16x16x32_bf16 v[158:161], v[100:103], v[142:145], 0
	ds_read_b128 v[142:145], v204 offset:128
	ds_read_b128 v[162:165], v205 offset:64
	ds_read_b128 v[206:209], v205 offset:80
	ds_read_b128 v[228:231], v204 offset:192
	ds_read_b128 v[238:241], v205 offset:96
	ds_read_b128 v[242:245], v205 offset:112
	s_waitcnt lgkmcnt(4)
	v_mfma_f32_16x16x32_bf16 v[142:145], v[20:23], v[162:165], v[142:145]
	s_waitcnt lgkmcnt(1)
	v_mfma_f32_16x16x32_bf16 v[162:165], v[28:31], v[238:241], v[228:231]
	v_mfma_f32_16x16x32_bf16 v[142:145], v[24:27], v[206:209], v[142:145]
	s_waitcnt lgkmcnt(0)
	v_mfma_f32_16x16x32_bf16 v[162:165], v[32:35], v[242:245], v[162:165]
	s_nop 5
	v_cvt_pk_bf16_f32 v142, v142, v143
	v_cvt_pk_bf16_f32 v143, v144, v145
	v_cvt_pk_bf16_f32 v144, v162, v163
	v_cvt_pk_bf16_f32 v145, v164, v165
	v_cndmask_b32_e64 v166, v166, v145, s[40:41]
	v_cndmask_b32_e64 v141, v141, v144, s[40:41]
	v_mfma_f32_16x16x32_bf16 v[146:149], v[56:59], v[142:145], v[146:149]
	v_cndmask_b32_e64 v190, v190, v143, s[40:41]
	v_cndmask_b32_e64 v167, v167, v142, s[40:41]
	v_mfma_f32_16x16x32_bf16 v[150:153], v[72:75], v[142:145], v[150:153]
	v_mfma_f32_16x16x32_bf16 v[154:157], v[88:91], v[142:145], v[154:157]
	v_mfma_f32_16x16x32_bf16 v[158:161], v[104:107], v[142:145], v[158:161]
	ds_read_b128 v[142:145], v204 offset:256
	ds_read_b128 v[162:165], v205 offset:128
	ds_read_b128 v[206:209], v205 offset:144
	ds_read_b128 v[228:231], v204 offset:320
	ds_read_b128 v[238:241], v205 offset:160
	ds_read_b128 v[242:245], v205 offset:176
	s_waitcnt lgkmcnt(4)
	v_mfma_f32_16x16x32_bf16 v[142:145], v[36:39], v[162:165], v[142:145]
	s_waitcnt lgkmcnt(1)
	v_mfma_f32_16x16x32_bf16 v[162:165], v[44:47], v[238:241], v[228:231]
	v_mfma_f32_16x16x32_bf16 v[142:145], v[40:43], v[206:209], v[142:145]
	v_add_u32_e32 v206, 0x21a00, v140
	v_add_u32_e32 v207, 0x22200, v140
	s_waitcnt lgkmcnt(0)
	v_mfma_f32_16x16x32_bf16 v[162:165], v[48:51], v[242:245], v[162:165]
	s_nop 3
	v_cvt_pk_bf16_f32 v142, v142, v143
	v_cvt_pk_bf16_f32 v143, v144, v145
	s_nop 1
	v_cvt_pk_bf16_f32 v144, v162, v163
	v_cvt_pk_bf16_f32 v145, v164, v165
	v_cndmask_b32_e64 v141, v141, v144, s[42:43]
	v_cndmask_b32_e64 v166, v166, v145, s[42:43]
	v_mfma_f32_16x16x32_bf16 v[146:149], v[60:63], v[142:145], v[146:149]
	v_mfma_f32_16x16x32_bf16 v[162:165], v[76:79], v[142:145], v[150:153]
	v_mfma_f32_16x16x32_bf16 v[228:231], v[92:95], v[142:145], v[154:157]
	v_mfma_f32_16x16x32_bf16 v[156:159], v[108:111], v[142:145], v[158:161]
	s_nop 2
	v_cndmask_b32_e64 v160, v167, v142, s[42:43]
	v_cndmask_b32_e64 v161, v190, v143, s[42:43]
	ds_read_b128 v[142:145], v204 offset:384
	ds_read_b128 v[150:153], v205 offset:192
	ds_read_b128 v[238:241], v205 offset:208
	ds_read_b128 v[208:211], v204 offset:448
	ds_read_b128 v[242:245], v205 offset:224
	ds_read_b128 v[246:249], v205 offset:240
	ds_read_b128 v[190:193], v206
	s_waitcnt lgkmcnt(0)
	v_mfma_f32_16x16x32_bf16 v[142:145], v[190:193], v[150:153], v[142:145]
	ds_read_b128 v[150:153], v207
	s_waitcnt lgkmcnt(0)
	v_mfma_f32_16x16x32_bf16 v[150:153], v[150:153], v[242:245], v[208:211]
	s_nop 2
	v_add_u32_e32 v208, 0x21e00, v140
	ds_read_b128 v[190:193], v208
	v_add_u32_e32 v209, 0x22600, v140
	s_waitcnt lgkmcnt(0)
	v_mfma_f32_16x16x32_bf16 v[142:145], v[190:193], v[238:241], v[142:145]
	ds_read_b128 v[190:193], v209
	s_waitcnt lgkmcnt(0)
	v_mfma_f32_16x16x32_bf16 v[150:153], v[190:193], v[246:249], v[150:153]
	s_nop 4
	v_cvt_pk_bf16_f32 v190, v142, v143
	v_cvt_pk_bf16_f32 v191, v144, v145
	s_nop 0
	v_cvt_pk_bf16_f32 v192, v150, v151
	v_cvt_pk_bf16_f32 v193, v152, v153
	v_cndmask_b32_e64 v219, v141, v192, s[44:45]
	v_cndmask_b32_e64 v218, v166, v193, s[44:45]
	v_mfma_f32_16x16x32_bf16 v[140:143], v[112:115], v[190:193], v[156:159]
	s_nop 2
	v_cndmask_b32_e64 v156, v161, v191, s[44:45]
	v_lshlrev_b32_e32 v215, 16, v156
	v_and_b32_e32 v216, 0xffff0000, v156
	v_lshlrev_b32_e32 v156, 2, v217
	v_add_u32_e32 v210, s6, v156
	v_mfma_f32_16x16x32_bf16 v[152:155], v[64:67], v[190:193], v[146:149]
	v_add_u32_e32 v211, s53, v156
	v_cndmask_b32_e64 v157, v160, v190, s[44:45]
	v_add_u32_e32 v212, s54, v156
	v_mfma_f32_16x16x32_bf16 v[144:147], v[80:83], v[190:193], v[162:165]
	v_lshlrev_b32_e32 v221, 16, v157
	v_and_b32_e32 v214, 0xffff0000, v157
	ds_read_b128 v[156:159], v212
	ds_read_b128 v[164:167], v210
	ds_read_b128 v[160:163], v211
	v_mfma_f32_16x16x32_bf16 v[148:151], v[96:99], v[190:193], v[228:231]
	s_waitcnt lgkmcnt(1)
	v_add_f32_e32 v152, v152, v164
	v_exp_f32_e32 v152, v152
	v_and_b32_e32 v164, 0xffff0000, v219
	s_waitcnt lgkmcnt(0)
	s_nop 2
	v_add_f32_e32 v148, v148, v160
	v_exp_f32_e32 v148, v148
	v_add_f32_e32 v152, 1.0, v152
	v_rcp_f32_e64 v152, -v152
	v_add_f32_e32 v149, v149, v161
	v_add_f32_e32 v148, 1.0, v148
	v_rcp_f32_e32 v148, v148
	v_mul_f32_e32 v152, v156, v152
	v_exp_f32_e32 v190, v152
	v_exp_f32_e32 v149, v149
	v_mul_f32_e32 v148, v148, v221
	v_or_b32_e32 v161, 16, v217
	v_fma_f32 v152, -v190, v190, 1.0
	v_max_f32_e32 v152, 0, v152
	v_sqrt_f32_e32 v152, v152
	v_add_f32_e32 v149, 1.0, v149
	v_rcp_f32_e32 v149, v149
	v_mul_f32_e32 v191, v148, v152
	v_mul_u32_u24_e32 v148, 0x210, v213
	v_add_lshl_u32 v160, v220, v148, 3
	v_add_f32_e32 v148, v153, v165
	v_exp_f32_e32 v148, v148
	v_mul_f32_e32 v149, v149, v214
	v_add_u32_e32 v213, s98, v160
	ds_write_b64 v213, v[190:191]
	v_add_f32_e32 v148, 1.0, v148
	v_rcp_f32_e64 v148, -v148
	v_lshlrev_b32_e32 v165, 16, v218
	v_mul_f32_e32 v148, v157, v148
	v_exp_f32_e32 v148, v148
	s_nop 0
	v_fma_f32 v152, -v148, v148, 1.0
	v_max_f32_e32 v152, 0, v152
	v_sqrt_f32_e32 v152, v152
	s_nop 0
	v_mul_f32_e32 v149, v149, v152
	v_add_u32_e32 v152, 0x420, v160
	v_add_u32_e32 v214, s98, v152
	ds_write_b64 v214, v[148:149]
	v_add_f32_e32 v148, v154, v166
	v_exp_f32_e32 v148, v148
	v_add_f32_e32 v149, v150, v162
	v_exp_f32_e32 v149, v149
	v_and_b32_e32 v166, 0xffff0000, v218
	v_add_f32_e32 v148, 1.0, v148
	v_rcp_f32_e64 v148, -v148
	v_add_f32_e32 v149, 1.0, v149
	v_rcp_f32_e32 v149, v149
	v_mul_f32_e32 v148, v158, v148
	v_exp_f32_e32 v148, v148
	v_mul_f32_e32 v149, v149, v215
	v_fma_f32 v150, -v148, v148, 1.0
	v_max_f32_e32 v150, 0, v150
	v_sqrt_f32_e32 v150, v150
	s_nop 0
	v_mul_f32_e32 v149, v149, v150
	v_add_u32_e32 v150, 0x840, v160
	v_add_u32_e32 v215, s98, v150
	ds_write_b64 v215, v[148:149]
	v_add_f32_e32 v148, v155, v167
	v_exp_f32_e32 v148, v148
	v_add_f32_e32 v149, v151, v163
	v_exp_f32_e32 v149, v149
	v_lshlrev_b32_e32 v163, 16, v219
	v_add_f32_e32 v148, 1.0, v148
	v_rcp_f32_e64 v148, -v148
	v_add_f32_e32 v149, 1.0, v149
	v_rcp_f32_e32 v149, v149
	v_mul_f32_e32 v148, v159, v148
	v_exp_f32_e32 v148, v148
	v_mul_f32_e32 v149, v149, v216
	v_fma_f32 v150, -v148, v148, 1.0
	v_max_f32_e32 v150, 0, v150
	v_sqrt_f32_e32 v150, v150
	s_nop 0
	v_mul_f32_e32 v149, v149, v150
	v_add_u32_e32 v150, 0xc60, v160
	v_add_u32_e32 v216, s98, v150
	ds_write_b64 v216, v[148:149]
	v_lshlrev_b32_e32 v148, 2, v161
	v_add_u32_e32 v217, s6, v148
	ds_read_b128 v[156:159], v217
	v_add_u32_e32 v218, s53, v148
	ds_read_b128 v[152:155], v218
	v_add_u32_e32 v219, s54, v148
	ds_read_b128 v[148:151], v219
	s_waitcnt lgkmcnt(2)
	v_add_f32_e32 v144, v144, v156
	v_exp_f32_e32 v144, v144
	s_waitcnt lgkmcnt(1)
	v_add_f32_e32 v140, v140, v152
	v_exp_f32_e32 v140, v140
	v_add_f32_e32 v141, v141, v153
	v_add_f32_e32 v144, 1.0, v144
	v_rcp_f32_e64 v144, -v144
	v_add_f32_e32 v140, 1.0, v140
	v_rcp_f32_e32 v140, v140
	v_exp_f32_e32 v141, v141
	s_waitcnt lgkmcnt(0)
	v_mul_f32_e32 v144, v148, v144
	v_exp_f32_e32 v162, v144
	v_mul_f32_e32 v140, v140, v163
	v_add_f32_e32 v141, 1.0, v141
	v_rcp_f32_e32 v141, v141
	v_fma_f32 v144, -v162, v162, 1.0
	v_max_f32_e32 v144, 0, v144
	v_sqrt_f32_e32 v144, v144
	v_mul_f32_e32 v141, v141, v164
	v_mul_f32_e32 v163, v140, v144
	v_mul_u32_u24_e32 v140, 0x84, v161
	v_add_lshl_u32 v140, v140, v220, 3
	v_add_u32_e32 v220, s98, v140
	v_add_f32_e32 v140, v145, v157
	v_exp_f32_e32 v140, v140
	ds_write_b64 v220, v[162:163]
	v_mov_b32_e32 v161, v1
	v_add_f32_e32 v140, 1.0, v140
	v_rcp_f32_e64 v140, -v140
	s_nop 0
	v_mul_f32_e32 v140, v149, v140
	v_exp_f32_e32 v140, v140
	s_nop 0
	v_fma_f32 v144, -v140, v140, 1.0
	v_max_f32_e32 v144, 0, v144
	v_sqrt_f32_e32 v144, v144
	s_nop 0
	v_mul_f32_e32 v141, v141, v144
	v_add_u32_e32 v144, 0x4620, v160
	v_add_u32_e32 v221, s98, v144
	ds_write_b64 v221, v[140:141]
	v_add_f32_e32 v140, v146, v158
	v_exp_f32_e32 v140, v140
	v_add_f32_e32 v141, v142, v154
	v_exp_f32_e32 v141, v141
	v_add_f32_e32 v140, 1.0, v140
	v_rcp_f32_e64 v140, -v140
	v_add_f32_e32 v141, 1.0, v141
	v_rcp_f32_e32 v141, v141
	v_mul_f32_e32 v140, v150, v140
	v_exp_f32_e32 v140, v140
	v_mul_f32_e32 v141, v141, v165
	v_fma_f32 v142, -v140, v140, 1.0
	v_max_f32_e32 v142, 0, v142
	v_sqrt_f32_e32 v142, v142
	s_nop 0
	v_mul_f32_e32 v141, v141, v142
	v_add_u32_e32 v142, 0x4a40, v160
	v_add_u32_e32 v222, s98, v142
	ds_write_b64 v222, v[140:141]
	v_add_f32_e32 v140, v147, v159
	v_exp_f32_e32 v140, v140
	v_add_f32_e32 v141, v143, v155
	v_exp_f32_e32 v141, v141
	v_add_f32_e32 v140, 1.0, v140
	v_rcp_f32_e64 v140, -v140
	v_add_f32_e32 v141, 1.0, v141
	v_rcp_f32_e32 v141, v141
	v_mul_f32_e32 v140, v151, v140
	v_exp_f32_e32 v140, v140
	v_mul_f32_e32 v141, v141, v166
	v_fma_f32 v142, -v140, v140, 1.0
	v_max_f32_e32 v142, 0, v142
	v_sqrt_f32_e32 v142, v142
	s_nop 0
	v_mul_f32_e32 v141, v141, v142
	v_add_u32_e32 v142, 0x4e60, v160
	v_add_u32_e32 v223, s98, v142
	ds_write_b64 v223, v[140:141]
	s_waitcnt lgkmcnt(0)
	s_barrier
	ds_read_b128 v[148:151], v224
	ds_read_b128 v[152:155], v224 offset:16
	ds_read_b128 v[144:147], v224 offset:32
	ds_read_b128 v[140:143], v224 offset:48
	s_waitcnt lgkmcnt(3)
	v_fma_f32 v149, 0, v148, v149
	v_fma_f32 v156, v150, v149, v151
	v_mul_f32_e32 v157, v148, v150
	s_waitcnt lgkmcnt(2)
	v_fma_f32 v158, v152, v156, v153
	v_mul_f32_e32 v159, v157, v152
	v_mul_f32_e32 v160, v154, v159
	v_fmac_f32_e32 v155, v154, v158
	s_waitcnt lgkmcnt(1)
	v_fma_f32 v145, v144, v155, v145
	v_mul_f32_e32 v144, v144, v160
	v_mul_f32_e32 v154, v146, v144
	v_fmac_f32_e32 v147, v146, v145
	s_waitcnt lgkmcnt(0)
	v_fma_f32 v141, v140, v147, v141
	v_mul_f32_e32 v140, v140, v154
	v_mul_f32_e32 v146, v142, v140
	v_fmac_f32_e32 v143, v142, v141
	v_mov_b32_e32 v142, 1.0
	v_mov_b32_e32 v150, v1
	v_mov_b32_e32 v151, 1.0
	v_mov_b32_dpp v142, v146 row_shr:1 row_mask:0xf bank_mask:0xf
	v_mov_b32_dpp v150, v143 row_shr:1 row_mask:0xf bank_mask:0xf
	v_fma_f32 v150, v146, v150, v143
	v_mul_f32_e32 v142, v146, v142
	v_mov_b32_e32 v152, v1
	s_nop 0
	v_mov_b32_dpp v151, v142 row_shr:2 row_mask:0xf bank_mask:0xf
	v_mov_b32_dpp v152, v150 row_shr:2 row_mask:0xf bank_mask:0xf
	v_fmac_f32_e32 v150, v142, v152
	v_mul_f32_e32 v142, v142, v151
	v_mov_b32_e32 v151, 1.0
	v_mov_b32_e32 v152, v1
	s_nop 0
	v_mov_b32_dpp v151, v142 row_shr:4 row_mask:0xf bank_mask:0xf
	v_mov_b32_dpp v152, v150 row_shr:4 row_mask:0xf bank_mask:0xf
	v_fmac_f32_e32 v150, v142, v152
	v_mul_f32_e32 v142, v142, v151
	v_mov_b32_e32 v151, 1.0
	v_mov_b32_e32 v152, v1
	s_nop 0
	v_mov_b32_dpp v151, v142 row_shr:8 row_mask:0xf bank_mask:0xf
	v_mov_b32_dpp v152, v150 row_shr:8 row_mask:0xf bank_mask:0xf
	v_fmac_f32_e32 v150, v142, v152
	v_mul_f32_e32 v142, v142, v151
	v_mov_b32_e32 v151, 1.0
	v_mov_b32_dpp v161, v150 row_shr:1 row_mask:0xf bank_mask:0xf
	v_fmac_f32_e32 v150, 0, v142
	v_mov_b32_dpp v151, v142 row_shr:1 row_mask:0xf bank_mask:0xf
	v_fmac_f32_e32 v161, 0, v151
	ds_bpermute_b32 v225, v196, v150
	ds_read_b128 v[150:153], v226
	v_fmac_f32_e32 v145, v144, v161
	v_fmac_f32_e32 v149, v148, v161
	v_fmac_f32_e32 v147, v154, v161
	v_fmac_f32_e32 v141, v140, v161
	s_waitcnt lgkmcnt(0)
	v_lshlrev_b32_e32 v163, 16, v152
	v_lshlrev_b32_e32 v142, 16, v150
	v_mul_f32_e32 v144, v145, v163
	v_mul_f32_e32 v145, 0xbfb8aa3b, v163
	v_mul_f32_e32 v148, v149, v142
	v_mul_f32_e32 v142, 0xbfb8aa3b, v142
	v_exp_f32_e32 v145, v145
	v_exp_f32_e32 v142, v142
	v_and_b32_e32 v150, 0xffff0000, v150
	v_and_b32_e32 v152, 0xffff0000, v152
	v_add_f32_e32 v145, 1.0, v145
	v_add_f32_e32 v142, 1.0, v142
	v_rcp_f32_e32 v145, v145
	v_rcp_f32_e32 v142, v142
	v_lshlrev_b32_e32 v164, 16, v153
	v_lshlrev_b32_e32 v162, 16, v151
	v_fmac_f32_e32 v156, v157, v161
	v_mul_f32_e32 v149, 0xbfb8aa3b, v150
	v_mul_f32_e32 v144, v144, v145
	v_mul_f32_e32 v145, v147, v152
	v_mul_f32_e32 v147, 0xbfb8aa3b, v152
	v_mul_f32_e32 v140, v141, v164
	v_mul_f32_e32 v141, 0xbfb8aa3b, v164
	v_mul_f32_e32 v142, v148, v142
	v_mul_f32_e32 v148, v156, v150
	v_exp_f32_e32 v149, v149
	v_mul_f32_e32 v150, 0xbfb8aa3b, v162
	v_exp_f32_e32 v147, v147
	v_exp_f32_e32 v141, v141
	v_exp_f32_e32 v150, v150
	v_add_f32_e32 v149, 1.0, v149
	v_add_f32_e32 v147, 1.0, v147
	v_add_f32_e32 v141, 1.0, v141
	v_rcp_f32_e32 v149, v149
	v_add_f32_e32 v150, 1.0, v150
	v_rcp_f32_e32 v147, v147
	v_rcp_f32_e32 v141, v141
	v_rcp_f32_e32 v150, v150
	v_and_b32_e32 v153, 0xffff0000, v153
	v_fmac_f32_e32 v158, v159, v161
	v_and_b32_e32 v151, 0xffff0000, v151
	v_mul_f32_e32 v148, v148, v149
	v_mul_f32_e32 v149, v158, v162
	v_fmac_f32_e32 v155, v160, v161
	v_mul_f32_e32 v145, v145, v147
	v_mul_f32_e32 v147, v140, v141
	v_mul_f32_e32 v141, 0xbfb8aa3b, v153
	v_mul_f32_e32 v149, v149, v150
	v_mul_f32_e32 v150, v155, v151
	v_mul_f32_e32 v151, 0xbfb8aa3b, v151
	v_exp_f32_e32 v141, v141
	v_exp_f32_e32 v151, v151
	v_fmac_f32_e32 v143, v146, v161
	v_mul_f32_e32 v140, v143, v153
	v_add_f32_e32 v141, 1.0, v141
	v_add_f32_e32 v151, 1.0, v151
	v_rcp_f32_e32 v141, v141
	v_rcp_f32_e32 v151, v151
	v_mul_f32_e32 v143, v140, v141
	v_mul_f32_e32 v150, v150, v151
	v_cvt_pk_bf16_f32 v140, v142, v148
	v_cvt_pk_bf16_f32 v141, v149, v150
	v_cvt_pk_bf16_f32 v142, v144, v145
	v_cvt_pk_bf16_f32 v143, v147, v143
	ds_write_b128 v227, v[140:143]
	s_waitcnt vmcnt(5)
	ds_write_b128 v177, v[124:127] offset:816
	s_waitcnt vmcnt(4)
	ds_write_b128 v179, v[128:131] offset:816
	s_waitcnt vmcnt(3)
	ds_write_b128 v181, v[132:135] offset:816
	s_waitcnt vmcnt(2)
	ds_write_b128 v199, v[136:139] offset:816
	s_and_saveexec_b64 s[10:11], s[38:39]
	ds_write_b128 v177, v[116:119]
	s_or_b64 exec, exec, s[10:11]
	s_lshl_b32 s7, s22, 3
	s_lshl_b32 s6, s23, 8
	s_and_b32 s7, s7, 0xc0
	s_or_b32 s6, s7, s6
	s_add_u32 s6, s6, s20
	s_addc_u32 s7, 0, s21
	v_and_b32_e32 v0, 3, v182
	v_lshl_add_u64 v[124:125], s[6:7], 0, v[184:185]
	v_lshlrev_b32_e32 v0, 4, v0
	v_lshl_add_u64 v[124:125], v[124:125], 0, v[0:1]
	v_mul_u32_u24_e32 v228, 0x110, v183
	v_lshl_add_u64 v[182:183], s[16:17], 0, v[124:125]
	s_movk_i32 s20, 0x100
	s_waitcnt vmcnt(0)
	v_readfirstlane_b32 s100, v172
	v_readfirstlane_b32 s101, v173
	v_and_b32_e32 v0, 15, v186
	v_lshlrev_b32_e32 v0, 4, v0
	v_subrev_u32_e32 v2, s100, v2
	v_lshl_add_u32 v2, v168, 11, v2
	v_lshl_or_b32 v174, v174, 11, v0
	v_lshl_or_b32 v176, v176, 11, v0
	v_lshl_or_b32 v178, v178, 11, v0
	v_lshl_or_b32 v180, v180, 11, v0
	v_add_u32_e32 v0, v171, v228
	v_lshrrev_b32_e32 v141, 6, v186
	v_and_b32_e32 v142, 63, v186
	v_and_b32_e32 v143, 15, v142
	v_lshrrev_b32_e32 v144, 4, v142
	v_lshl_or_b32 v145, v141, 4, v143
	v_mul_u32_u24_e32 v146, 0x1100, v144
	v_lshlrev_b32_e32 v147, 3, v145
	v_lshrrev_b32_e32 v148, 1, v141
	v_lshlrev_b32_e32 v148, 4, v148
	v_add3_u32 v213, v146, v147, v148
	v_add_u32_e32 v213, 0x11000, v213
	v_lshl_add_u32 v149, v141, 2, v144
	v_mul_u32_u24_e32 v150, 0x440, v149
	v_lshlrev_b32_e32 v151, 6, v143
	v_lshrrev_b32_e32 v152, 2, v143
	v_lshlrev_b32_e32 v152, 4, v152
	v_add3_u32 v224, v150, v151, v152
	v_add_u32_e32 v224, 0x11000, v224
	s_add_u32 s100, s100, 0x80000
	s_addc_u32 s101, s101, 0
	s_sub_u32 s6, s100, 0x1800
	s_subb_u32 s7, s101, 0
	global_load_dwordx4 v[124:127], v174, s[100:101]
	global_load_dwordx4 v[128:131], v176, s[100:101]
	global_load_dwordx4 v[132:135], v178, s[100:101]
	global_load_dwordx4 v[136:139], v180, s[100:101]
	s_and_saveexec_b64 s[10:11], s[38:39]
	s_cbranch_execz .Lrnn_pre_halo
	global_load_dwordx4 v[116:119], v174, s[6:7]

.Lrnn_wd:
	ds_write_b16 v175, v120
	ds_write_b16_d16_hi v175, v120 offset:272
	ds_write_b16 v175, v121 offset:544
	ds_write_b16_d16_hi v175, v121 offset:816
	ds_write_b16 v175, v122 offset:1088
	ds_write_b16_d16_hi v175, v122 offset:1360
	ds_write_b16 v175, v123 offset:1632
	ds_write_b16_d16_hi v175, v123 offset:1904
	s_nop 0
	global_load_dwordx4 v[120:123], v2, s[100:101]
	global_store_dwordx4 v[182:183], v[148:151], off
	v_cvt_pk_bf16_f32 v140, v140, v141
	v_cvt_pk_bf16_f32 v141, v142, v143
	v_cvt_pk_bf16_f32 v142, v160, v161
	v_cvt_pk_bf16_f32 v143, v162, v163
	v_cndmask_b32_e32 v229, 0, v140, vcc
	v_cndmask_b32_e32 v230, 0, v141, vcc
	v_mfma_f32_16x16x32_bf16 v[156:159], v[52:55], v[140:143], 0
	v_cndmask_b32_e32 v184, 0, v142, vcc
	v_cndmask_b32_e32 v185, 0, v143, vcc
	v_mfma_f32_16x16x32_bf16 v[144:147], v[68:71], v[140:143], 0
	v_mfma_f32_16x16x32_bf16 v[148:151], v[84:87], v[140:143], 0
	v_mfma_f32_16x16x32_bf16 v[152:155], v[100:103], v[140:143], 0
	s_waitcnt lgkmcnt(12)
	v_mfma_f32_16x16x32_bf16 v[200:203], v[20:23], v[190:193], v[200:203]
	s_waitcnt lgkmcnt(9)
	v_mfma_f32_16x16x32_bf16 v[164:167], v[28:31], v[242:245], v[164:167]
	v_mfma_f32_16x16x32_bf16 v[200:203], v[24:27], v[238:241], v[200:203]
	s_waitcnt lgkmcnt(0)
	v_mfma_f32_16x16x32_bf16 v[164:167], v[32:35], v[246:249], v[164:167]
	ds_read_b128 v[140:143], v204 offset:256
	ds_read_b128 v[190:193], v205 offset:128
	ds_read_b128 v[238:241], v205 offset:144
	ds_read_b128 v[160:163], v204 offset:320
	ds_read_b128 v[242:245], v205 offset:160
	ds_read_b128 v[246:249], v205 offset:176
	ds_read_b128 v[214:217], v206
	ds_read_b128 v[218:221], v207
	s_nop 1
	v_cvt_pk_bf16_f32 v200, v200, v201
	v_cvt_pk_bf16_f32 v201, v202, v203
	v_cvt_pk_bf16_f32 v202, v164, v165
	v_cvt_pk_bf16_f32 v203, v166, v167
	v_cndmask_b32_e64 v229, v229, v200, s[40:41]
	v_cndmask_b32_e64 v230, v230, v201, s[40:41]
	v_mfma_f32_16x16x32_bf16 v[156:159], v[56:59], v[200:203], v[156:159]
	v_cndmask_b32_e64 v184, v184, v202, s[40:41]
	v_cndmask_b32_e64 v185, v185, v203, s[40:41]
	v_mfma_f32_16x16x32_bf16 v[144:147], v[72:75], v[200:203], v[144:147]
	v_mfma_f32_16x16x32_bf16 v[148:151], v[88:91], v[200:203], v[148:151]
	v_mfma_f32_16x16x32_bf16 v[152:155], v[104:107], v[200:203], v[152:155]
	s_waitcnt lgkmcnt(6)
	v_mfma_f32_16x16x32_bf16 v[140:143], v[36:39], v[190:193], v[140:143]
	s_waitcnt lgkmcnt(3)
	v_mfma_f32_16x16x32_bf16 v[160:163], v[44:47], v[242:245], v[160:163]
	v_mfma_f32_16x16x32_bf16 v[140:143], v[40:43], v[238:241], v[140:143]
	s_waitcnt lgkmcnt(2)
	v_mfma_f32_16x16x32_bf16 v[160:163], v[48:51], v[246:249], v[160:163]
	ds_read_b128 v[200:203], v204 offset:384
	ds_read_b128 v[190:193], v205 offset:192
	ds_read_b128 v[238:241], v205 offset:208
	ds_read_b128 v[164:167], v204 offset:448
	ds_read_b128 v[242:245], v205 offset:224
	ds_read_b128 v[246:249], v205 offset:240
	s_nop 3
	v_cvt_pk_bf16_f32 v140, v140, v141
	v_cvt_pk_bf16_f32 v141, v142, v143
	v_cvt_pk_bf16_f32 v142, v160, v161
	v_cvt_pk_bf16_f32 v143, v162, v163
	v_cndmask_b32_e64 v229, v229, v140, s[42:43]
	v_cndmask_b32_e64 v230, v230, v141, s[42:43]
	v_mfma_f32_16x16x32_bf16 v[156:159], v[60:63], v[140:143], v[156:159]
	v_cndmask_b32_e64 v184, v184, v142, s[42:43]
	v_cndmask_b32_e64 v185, v185, v143, s[42:43]
	v_mfma_f32_16x16x32_bf16 v[144:147], v[76:79], v[140:143], v[144:147]
	v_mfma_f32_16x16x32_bf16 v[148:151], v[92:95], v[140:143], v[148:151]
	v_mfma_f32_16x16x32_bf16 v[152:155], v[108:111], v[140:143], v[152:155]
	ds_read_b128 v[140:143], v208
	ds_read_b128 v[160:163], v209
	s_waitcnt lgkmcnt(6)
	v_mfma_f32_16x16x32_bf16 v[200:203], v[214:217], v[190:193], v[200:203]
	s_waitcnt lgkmcnt(3)
	v_mfma_f32_16x16x32_bf16 v[164:167], v[218:221], v[242:245], v[164:167]
	s_waitcnt lgkmcnt(1)
	v_mfma_f32_16x16x32_bf16 v[200:203], v[140:143], v[238:241], v[200:203]
	s_waitcnt lgkmcnt(0)
	v_mfma_f32_16x16x32_bf16 v[164:167], v[160:163], v[246:249], v[164:167]
	ds_read_b128 v[190:193], v210
	ds_read_b128 v[238:241], v210 offset:128
	ds_read_b128 v[242:245], v210 offset:256
	ds_read_b128 v[246:249], v210 offset:64
	ds_read_b128 v[214:217], v210 offset:192
	ds_read_b128 v[218:221], v210 offset:320
	s_nop 3
	v_cvt_pk_bf16_f32 v200, v200, v201
	v_cvt_pk_bf16_f32 v201, v202, v203
	v_cvt_pk_bf16_f32 v202, v164, v165
	v_cvt_pk_bf16_f32 v203, v166, v167
	v_cndmask_b32_e64 v229, v229, v200, s[44:45]
	v_cndmask_b32_e64 v230, v230, v201, s[44:45]
	v_mfma_f32_16x16x32_bf16 v[156:159], v[64:67], v[200:203], v[156:159]
	v_cndmask_b32_e64 v184, v184, v202, s[44:45]
	v_cndmask_b32_e64 v185, v185, v203, s[44:45]
	v_mfma_f32_16x16x32_bf16 v[144:147], v[80:83], v[200:203], v[144:147]
	v_mfma_f32_16x16x32_bf16 v[148:151], v[96:99], v[200:203], v[148:151]
	v_mfma_f32_16x16x32_bf16 v[152:155], v[112:115], v[200:203], v[152:155]
	v_lshlrev_b32_e32 v231, 16, v229
	v_and_b32_e32 v229, 0xffff0000, v229
	v_lshlrev_b32_e32 v232, 16, v230
	v_and_b32_e32 v230, 0xffff0000, v230
	v_lshlrev_b32_e32 v228, 16, v184
	v_and_b32_e32 v184, 0xffff0000, v184
	v_lshlrev_b32_e32 v3, 16, v185
	v_and_b32_e32 v185, 0xffff0000, v185
	s_nop 1
	s_waitcnt lgkmcnt(5)
	v_add_f32_e32 v156, v156, v190
	v_add_f32_e32 v157, v157, v191
	v_add_f32_e32 v158, v158, v192
	v_add_f32_e32 v159, v159, v193
	s_waitcnt lgkmcnt(4)
	v_add_f32_e32 v148, v148, v238
	v_add_f32_e32 v149, v149, v239
	v_add_f32_e32 v150, v150, v240
	v_add_f32_e32 v151, v151, v241
	v_exp_f32_e32 v156, v156
	v_exp_f32_e32 v157, v157
	v_exp_f32_e32 v158, v158
	v_exp_f32_e32 v159, v159
	v_exp_f32_e32 v148, v148
	v_exp_f32_e32 v149, v149
	v_exp_f32_e32 v150, v150
	v_exp_f32_e32 v151, v151
	s_waitcnt lgkmcnt(2)
	v_add_f32_e32 v144, v144, v246
	v_add_f32_e32 v145, v145, v247
	v_add_f32_e32 v146, v146, v248
	v_add_f32_e32 v147, v147, v249
	s_waitcnt lgkmcnt(1)
	v_add_f32_e32 v152, v152, v214
	v_add_f32_e32 v153, v153, v215
	v_add_f32_e32 v154, v154, v216
	v_add_f32_e32 v155, v155, v217
	v_exp_f32_e32 v144, v144
	v_exp_f32_e32 v145, v145
	v_exp_f32_e32 v146, v146
	v_exp_f32_e32 v147, v147
	v_exp_f32_e32 v152, v152
	v_exp_f32_e32 v153, v153
	v_exp_f32_e32 v154, v154
	v_exp_f32_e32 v155, v155
	v_add_f32_e32 v156, 1.0, v156
	v_add_f32_e32 v157, 1.0, v157
	v_add_f32_e32 v158, 1.0, v158
	v_add_f32_e32 v159, 1.0, v159
	v_add_f32_e32 v144, 1.0, v144
	v_add_f32_e32 v145, 1.0, v145
	v_add_f32_e32 v146, 1.0, v146
	v_add_f32_e32 v147, 1.0, v147
	v_add_f32_e32 v148, 1.0, v148
	v_add_f32_e32 v149, 1.0, v149
	v_add_f32_e32 v150, 1.0, v150
	v_add_f32_e32 v151, 1.0, v151
	v_add_f32_e32 v152, 1.0, v152
	v_add_f32_e32 v153, 1.0, v153
	v_add_f32_e32 v154, 1.0, v154
	v_add_f32_e32 v155, 1.0, v155
	v_rcp_f32_e64 v156, -v156
	v_rcp_f32_e64 v157, -v157
	v_rcp_f32_e64 v158, -v158
	v_rcp_f32_e64 v159, -v159
	v_rcp_f32_e64 v144, -v144
	v_rcp_f32_e64 v145, -v145
	v_rcp_f32_e64 v146, -v146
	v_rcp_f32_e64 v147, -v147
	v_rcp_f32_e32 v148, v148
	v_rcp_f32_e32 v149, v149
	v_rcp_f32_e32 v150, v150
	v_rcp_f32_e32 v151, v151
	v_rcp_f32_e32 v152, v152
	v_rcp_f32_e32 v153, v153
	v_rcp_f32_e32 v154, v154
	v_rcp_f32_e32 v155, v155
	s_waitcnt lgkmcnt(0)
	v_mul_f32_e32 v156, v242, v156
	v_mul_f32_e32 v157, v243, v157
	v_mul_f32_e32 v158, v244, v158
	v_mul_f32_e32 v159, v245, v159
	v_mul_f32_e32 v144, v218, v144
	v_mul_f32_e32 v145, v219, v145
	v_mul_f32_e32 v146, v220, v146
	v_mul_f32_e32 v147, v221, v147
	v_mul_f32_e32 v148, v148, v231
	v_mul_f32_e32 v149, v149, v229
	v_mul_f32_e32 v150, v150, v232
	v_mul_f32_e32 v151, v151, v230
	v_mul_f32_e32 v152, v152, v228
	v_mul_f32_e32 v153, v153, v184
	v_mul_f32_e32 v154, v154, v3
	v_mul_f32_e32 v155, v155, v185
	v_exp_f32_e32 v238, v156
	v_exp_f32_e32 v240, v157
	v_exp_f32_e32 v242, v158
	v_exp_f32_e32 v244, v159
	v_exp_f32_e32 v214, v144
	v_exp_f32_e32 v216, v145
	v_exp_f32_e32 v218, v146
	v_exp_f32_e32 v220, v147
	v_fma_f32 v190, -v238, v238, 1.0
	v_fma_f32 v191, -v240, v240, 1.0
	v_fma_f32 v192, -v242, v242, 1.0
	v_fma_f32 v193, -v244, v244, 1.0
	v_fma_f32 v246, -v214, v214, 1.0
	v_fma_f32 v247, -v216, v216, 1.0
	v_fma_f32 v248, -v218, v218, 1.0
	v_fma_f32 v249, -v220, v220, 1.0
	v_sqrt_f32_e32 v190, v190
	v_sqrt_f32_e32 v191, v191
	v_sqrt_f32_e32 v192, v192
	v_sqrt_f32_e32 v193, v193
	v_sqrt_f32_e32 v246, v246
	v_sqrt_f32_e32 v247, v247
	v_sqrt_f32_e32 v248, v248
	v_sqrt_f32_e32 v249, v249
	v_mul_f32_e32 v239, v148, v190
	v_mul_f32_e32 v241, v149, v191
	v_mul_f32_e32 v243, v150, v192
	v_mul_f32_e32 v245, v151, v193
	v_mul_f32_e32 v215, v152, v246
	v_mul_f32_e32 v217, v153, v247
	v_mul_f32_e32 v219, v154, v248
	v_mul_f32_e32 v221, v155, v249
	ds_write_b64 v213, v[238:239]
	ds_write_b64 v213, v[240:241] offset:1088
	ds_write_b64 v213, v[242:243] offset:2176
	ds_write_b64 v213, v[244:245] offset:3264
	ds_write_b64 v213, v[214:215] offset:17408
	ds_write_b64 v213, v[216:217] offset:18496
	ds_write_b64 v213, v[218:219] offset:19584
	ds_write_b64 v213, v[220:221] offset:20672
	v_mov_b32_e32 v161, 0
	s_waitcnt lgkmcnt(0)
	s_barrier
	ds_read_b128 v[148:151], v224
	ds_read_b128 v[152:155], v224 offset:16
	ds_read_b128 v[144:147], v224 offset:32
	ds_read_b128 v[140:143], v224 offset:48
	s_waitcnt vmcnt(2)
	ds_write_b128 v177, v[124:127] offset:816
	ds_write_b128 v179, v[128:131] offset:816
	ds_write_b128 v181, v[132:135] offset:816
	ds_write_b128 v199, v[136:139] offset:816
	s_and_saveexec_b64 s[10:11], s[38:39]
	s_cbranch_execz .Lrnn_halo_done
	ds_write_b128 v177, v[116:119]
